# P1 workgroup de-phasing: half of the workgroups (bit 3 of the id) start the in-proj GEMM phase about 8 us late so the two groups' epilogue store bursts no longer coincide
# speedup vs baseline: 1.0020x; 1.0006x over previous
.LBB0_115:
	s_or_b64 exec, exec, s[0:1]
	s_add_u32 s10, s72, 0x14000000
	s_addc_u32 s11, s73, 0
	s_add_u32 s46, s72, 0x4000000
	s_addc_u32 s47, s73, 0
	s_add_u32 s78, s72, 0x6000000
	s_addc_u32 s79, s73, 0
	s_add_u32 s48, s72, 0x8000000
	s_addc_u32 s49, s73, 0
	s_add_u32 s6, s72, 0xa000000
	s_addc_u32 s7, s73, 0
	s_add_u32 s0, s72, 0xc000000
	s_addc_u32 s1, s73, 0
	s_waitcnt lgkmcnt(0)
	v_mov_b32_e32 v0, v165
	s_barrier
	s_bitcmp1_b32 s2, 3
	s_cbranch_scc0 .Ldph1_skip
	s_sleep 127
	s_sleep 127
.Ldph1_skip:
	s_cmpk_gt_i32 s2, 0x7ff
	v_readfirstlane_b32 s22, v0
	s_cbranch_scc1 .LBB0_147
	s_ashr_i32 s3, s2, 31
	s_lshr_b32 s4, s3, 29
	s_add_i32 s13, s2, s4
	s_and_b32 s4, s13, -8
	s_sub_i32 s14, s2, s4
	s_cmp_gt_i32 s14, -1
	s_cbranch_scc0 .LBB0_118
	s_lshl_b32 s12, s14, 8
	s_cbranch_execz .LBB0_119
	s_branch .LBB0_120
